# v88 + phase 1 plain-map epilogue: packed mul/add around exp/rcp, row*ld as a 64-bit shift instead of integer multiplies
# speedup vs baseline: 1.0263x; 1.0025x over previous
.LBB0_202:
	s_or_saveexec_b64 s[10:11], s[10:11]
	v_mov_b64_e32 v[10:11], s[66:67]
	v_mov_b64_e32 v[4:5], s[8:9]
	s_xor_b64 exec, exec, s[10:11]
	v_lshlrev_b32_e32 v2, 7, v141
	v_mov_b64_e32 v[10:11], 0x100
	v_mov_b64_e32 v[4:5], s[34:35]
	s_or_b64 s[68:69], s[68:69], exec
	s_or_b64 exec, exec, s[10:11]
	s_and_saveexec_b64 s[66:67], s[68:69]
	s_cbranch_execz .LBB0_84
	v_and_b32_e32 v6, 15, v157
	v_ashrrev_i32_e32 v3, 31, v2
	v_lshrrev_b32_e32 v44, 4, v140
	v_lshl_add_u64 v[2:3], v[2:3], 1, v[4:5]
	v_lshlrev_b32_e32 v0, 4, v6
	v_lshl_add_u64 v[12:13], v[2:3], 0, v[0:1]
	v_mul_u32_u24_e32 v0, 0x410, v44
	s_cmp_gt_u32 s63, 7
	v_add3_u32 v0, v159, v0, v158
	v_lshlrev_b32_e32 v2, 5, v6
	v_add_u32_e32 v26, 0x400, v219
	v_add_u32_e32 v27, 0x800, v219
	v_add_u32_e32 v28, 0xc00, v219
	v_add_u32_e32 v29, 0x4000, v219
	v_add_u32_e32 v30, 0x4400, v219
	v_add_u32_e32 v31, 0x4800, v219
	v_add_u32_e32 v32, 0x4c00, v219
	v_add_u32_e32 v40, 0x8000, v219
	v_add_u32_e32 v33, 0x8400, v219
	v_add_u32_e32 v34, 0x8800, v219
	v_add_u32_e32 v36, 0x8c00, v219
	v_add_u32_e32 v41, 0xc000, v219
	v_add_u32_e32 v37, 0xc400, v219
	v_add_u32_e32 v38, 0xc800, v219
	v_add_u32_e32 v39, 0xcc00, v219
	v_add_u32_e32 v42, 0x9000, v219
	v_add_u32_e32 v43, 0xd000, v219
	s_cselect_b64 s[68:69], -1, 0
	s_mov_b32 s63, 0
	v_cmp_eq_u32_e64 s[8:9], 0, v6
	v_add3_u32 v0, v0, v2, 0
	v_add3_u32 v14, v44, s62, v156
	s_waitcnt lgkmcnt(0)
	s_barrier
	ds_write2_b32 v219, v163, v167 offset1:16
	ds_write2_b32 v26, v162, v166 offset0:4 offset1:20
	ds_write2_b32 v27, v161, v165 offset0:8 offset1:24
	ds_write2_b32 v28, v160, v164 offset0:12 offset1:28
	ds_write2_b32 v29, v171, v175 offset0:64 offset1:80
	ds_write2_b32 v30, v170, v174 offset0:68 offset1:84
	ds_write2_b32 v31, v169, v173 offset0:72 offset1:88
	ds_write2_b32 v32, v168, v172 offset0:76 offset1:92
	ds_write2_b32 v40, v180, v185 offset0:128 offset1:144
	ds_write2_b32 v33, v179, v184 offset0:132 offset1:148
	ds_write2_b32 v34, v178, v183 offset0:136 offset1:152
	ds_write2_b32 v36, v177, v182 offset0:140 offset1:156
	ds_write2_b32 v41, v189, v193 offset0:192 offset1:208
	ds_write2_b32 v37, v188, v192 offset0:196 offset1:212
	ds_write2_b32 v38, v187, v191 offset0:200 offset1:216
	ds_write2_b32 v39, v186, v190 offset0:204 offset1:220
	ds_write2_b32 v219, v128, v124 offset0:128 offset1:144
	ds_write2_b32 v26, v129, v125 offset0:132 offset1:148
	ds_write2_b32 v27, v130, v126 offset0:136 offset1:152
	ds_write2_b32 v28, v131, v127 offset0:140 offset1:156
	ds_write2_b32 v29, v120, v132 offset0:192 offset1:208
	ds_write2_b32 v30, v121, v117 offset0:196 offset1:212
	ds_write2_b32 v31, v122, v118 offset0:200 offset1:216
	ds_write2_b32 v32, v123, v119 offset0:204 offset1:220
	ds_write2_b32 v33, v134, v138 offset1:16
	ds_write2_b32 v34, v135, v139 offset0:4 offset1:20
	ds_write2_b32 v36, v136, v144 offset0:8 offset1:24
	ds_write2_b32 v42, v133, v137 offset0:12 offset1:28
	ds_write2_b32 v37, v146, v181 offset0:64 offset1:80
	ds_write2_b32 v38, v147, v149 offset0:68 offset1:84
	ds_write2_b32 v39, v176, v150 offset0:72 offset1:88
	ds_write2_b32 v43, v145, v148 offset0:76 offset1:92
	s_waitcnt lgkmcnt(0)
	s_barrier
	v_mov_b32_e32 v228, 0xbfb8aa3b
	v_mov_b32_e32 v229, 0xbfb8aa3b
	v_mov_b32_e32 v230, 1.0
	v_mov_b32_e32 v231, 1.0
	v_ffbl_b32_e32 v232, v10
	s_branch .LBB0_208

.LBB0_207:
	s_or_b64 exec, exec, s[70:71]
	s_waitcnt lgkmcnt(1)
	v_ashrrev_i32_e32 v6, 31, v24
	v_mov_b32_e32 v8, v24
	v_ashrrev_i32_e32 v9, 31, v24
	v_lshlrev_b64 v[6:7], v232, v[8:9]
	s_addk_i32 s63, 0x2080
	s_waitcnt lgkmcnt(0)
	v_cvt_pk_bf16_f32 v2, v16, v17
	v_cvt_pk_bf16_f32 v3, v18, v19
	v_cvt_pk_bf16_f32 v4, v20, v21
	v_cvt_pk_bf16_f32 v5, v22, v23
	v_lshl_add_u64 v[6:7], v[6:7], 1, v[12:13]
	s_cmpk_lg_u32 s63, 0x8200
	v_add_u32_e32 v14, 8, v14
	global_store_dwordx4 v[6:7], v[2:5], off
	s_cbranch_scc0 .LBB0_227
.LBB0_208:
	v_add_u32_e32 v24, s63, v0
	ds_read_b128 v[6:9], v24
	ds_read_b128 v[2:5], v24 offset:16
	v_cndmask_b32_e64 v15, 0, 1, s[68:69]
	v_cmp_ne_u32_e64 s[10:11], 1, v15
	s_and_saveexec_b64 s[70:71], s[6:7]
	s_xor_b64 s[70:71], exec, s[70:71]
	s_cbranch_execz .LBB0_214
	s_waitcnt lgkmcnt(0)
	v_pk_mul_f32 v[16:17], v[6:7], v[228:229]
	v_pk_mul_f32 v[18:19], v[8:9], v[228:229]
	v_pk_mul_f32 v[20:21], v[2:3], v[228:229]
	v_pk_mul_f32 v[22:23], v[4:5], v[228:229]
	v_exp_f32_e32 v16, v16
	v_exp_f32_e32 v17, v17
	v_exp_f32_e32 v18, v18
	v_exp_f32_e32 v19, v19
	v_exp_f32_e32 v20, v20
	v_exp_f32_e32 v21, v21
	v_exp_f32_e32 v22, v22
	v_exp_f32_e32 v23, v23
	v_pk_add_f32 v[16:17], v[16:17], v[230:231]
	v_pk_add_f32 v[18:19], v[18:19], v[230:231]
	v_pk_add_f32 v[20:21], v[20:21], v[230:231]
	v_pk_add_f32 v[22:23], v[22:23], v[230:231]
	v_rcp_f32_e32 v16, v16
	v_rcp_f32_e32 v17, v17
	v_rcp_f32_e32 v18, v18
	v_rcp_f32_e32 v19, v19
	v_rcp_f32_e32 v20, v20
	v_rcp_f32_e32 v21, v21
	v_rcp_f32_e32 v22, v22
	v_rcp_f32_e32 v23, v23
	s_and_b64 vcc, exec, s[10:11]
	s_cbranch_vccz .Lsg_done_a
	v_pk_mul_f32 v[16:17], v[6:7], v[16:17]
	v_pk_mul_f32 v[18:19], v[8:9], v[18:19]
	v_pk_mul_f32 v[20:21], v[2:3], v[20:21]
	v_pk_mul_f32 v[22:23], v[4:5], v[22:23]
.Lsg_done_a:
.LBB0_213:
.LBB0_214:
	s_andn2_saveexec_b64 s[70:71], s[70:71]
	s_cbranch_execz .LBB0_218
	s_waitcnt lgkmcnt(1)
	v_mul_f32_e32 v15, v7, v7
	v_fmac_f32_e32 v15, v6, v6
	v_fmac_f32_e32 v15, v8, v8
	v_fmac_f32_e32 v15, v9, v9
	s_waitcnt lgkmcnt(0)
	v_fmac_f32_e32 v15, v2, v2
	v_fmac_f32_e32 v15, v3, v3
	v_fmac_f32_e32 v15, v4, v4
	v_fmac_f32_e32 v15, v5, v5
	s_nop 1
	v_add_f32_dpp v15, v15, v15 quad_perm:[1,0,3,2] row_mask:0xf bank_mask:0xf bound_ctrl:1
	s_nop 1
	v_add_f32_dpp v15, v15, v15 quad_perm:[2,3,0,1] row_mask:0xf bank_mask:0xf bound_ctrl:1
	s_nop 1
	v_add_f32_dpp v15, v15, v15 row_half_mirror row_mask:0xf bank_mask:0xf bound_ctrl:1
	s_nop 1
	v_mov_b32_dpp v16, v15 row_mirror row_mask:0xf bank_mask:0xf bound_ctrl:1
	s_and_saveexec_b64 s[72:73], s[8:9]
	s_cbranch_execz .LBB0_217
	v_add_f32_e32 v18, v15, v16
	v_ashrrev_i32_e32 v15, 31, v14
	v_lshl_add_u64 v[16:17], v[14:15], 2, s[36:37]
	global_atomic_add_f32 v[16:17], v18, off

.LBB0_218:
	s_or_b64 exec, exec, s[70:71]
	s_waitcnt lgkmcnt(1)
	v_ashrrev_i32_e32 v6, 31, v14
	v_mov_b32_e32 v8, v14
	v_ashrrev_i32_e32 v9, 31, v14
	v_lshlrev_b64 v[6:7], v232, v[8:9]
	s_waitcnt lgkmcnt(0)
	v_cvt_pk_bf16_f32 v2, v16, v17
	v_cvt_pk_bf16_f32 v3, v18, v19
	v_cvt_pk_bf16_f32 v4, v20, v21
	v_cvt_pk_bf16_f32 v5, v22, v23
	v_lshl_add_u64 v[6:7], v[6:7], 1, v[12:13]
	global_store_dwordx4 v[6:7], v[2:5], off
	ds_read_b128 v[6:9], v24 offset:4160
	ds_read_b128 v[2:5], v24 offset:4176
	s_and_saveexec_b64 s[70:71], s[6:7]
	s_xor_b64 s[70:71], exec, s[70:71]
	s_cbranch_execz .LBB0_224
	s_waitcnt lgkmcnt(0)
	v_pk_mul_f32 v[16:17], v[6:7], v[228:229]
	v_pk_mul_f32 v[18:19], v[8:9], v[228:229]
	v_pk_mul_f32 v[20:21], v[2:3], v[228:229]
	v_pk_mul_f32 v[22:23], v[4:5], v[228:229]
	v_exp_f32_e32 v16, v16
	v_exp_f32_e32 v17, v17
	v_exp_f32_e32 v18, v18
	v_exp_f32_e32 v19, v19
	v_exp_f32_e32 v20, v20
	v_exp_f32_e32 v21, v21
	v_exp_f32_e32 v22, v22
	v_exp_f32_e32 v23, v23
	v_pk_add_f32 v[16:17], v[16:17], v[230:231]
	v_pk_add_f32 v[18:19], v[18:19], v[230:231]
	v_pk_add_f32 v[20:21], v[20:21], v[230:231]
	v_pk_add_f32 v[22:23], v[22:23], v[230:231]
	v_rcp_f32_e32 v16, v16
	v_rcp_f32_e32 v17, v17
	v_rcp_f32_e32 v18, v18
	v_rcp_f32_e32 v19, v19
	v_rcp_f32_e32 v20, v20
	v_rcp_f32_e32 v21, v21
	v_rcp_f32_e32 v22, v22
	v_rcp_f32_e32 v23, v23
	s_and_b64 vcc, exec, s[10:11]
	s_cbranch_vccz .Lsg_done_b
	v_pk_mul_f32 v[16:17], v[6:7], v[16:17]
	v_pk_mul_f32 v[18:19], v[8:9], v[18:19]
	v_pk_mul_f32 v[20:21], v[2:3], v[20:21]
	v_pk_mul_f32 v[22:23], v[4:5], v[22:23]
.Lsg_done_b:
.LBB0_223:
.LBB0_224:
	s_or_saveexec_b64 s[70:71], s[70:71]
	v_add_u32_e32 v24, 4, v14
	s_xor_b64 exec, exec, s[70:71]
	s_cbranch_execz .LBB0_207
	s_waitcnt lgkmcnt(1)
	v_mul_f32_e32 v15, v7, v7
	v_fmac_f32_e32 v15, v6, v6
	v_fmac_f32_e32 v15, v8, v8
	v_fmac_f32_e32 v15, v9, v9
	s_waitcnt lgkmcnt(0)
	v_fmac_f32_e32 v15, v2, v2
	v_fmac_f32_e32 v15, v3, v3
	v_fmac_f32_e32 v15, v4, v4
	v_fmac_f32_e32 v15, v5, v5
	s_nop 1
	v_add_f32_dpp v15, v15, v15 quad_perm:[1,0,3,2] row_mask:0xf bank_mask:0xf bound_ctrl:1
	s_nop 1
	v_add_f32_dpp v15, v15, v15 quad_perm:[2,3,0,1] row_mask:0xf bank_mask:0xf bound_ctrl:1
	s_nop 1
	v_add_f32_dpp v15, v15, v15 row_half_mirror row_mask:0xf bank_mask:0xf bound_ctrl:1
	s_nop 1
	v_mov_b32_dpp v16, v15 row_mirror row_mask:0xf bank_mask:0xf bound_ctrl:1
	s_and_saveexec_b64 s[72:73], s[8:9]
	s_cbranch_execz .LBB0_206
	v_ashrrev_i32_e32 v25, 31, v24
	v_add_f32_e32 v15, v15, v16
	v_lshl_add_u64 v[16:17], v[24:25], 2, s[36:37]
	global_atomic_add_f32 v[16:17], v15, off
	s_branch .LBB0_206
.LBB0_227:
	s_andn2_b64 vcc, exec, s[64:65]
	s_cbranch_vccnz .LBB0_84
	s_waitcnt lgkmcnt(0)
	v_add_u32_e32 v2, s62, v44
	s_movk_i32 s62, 0x84
	v_add3_u32 v14, v2, v156, s62
	s_mov_b32 s68, 0
	s_barrier
	ds_write2_b32 v219, v64, v68 offset1:16
	ds_write2_b32 v26, v65, v69 offset0:4 offset1:20
	ds_write2_b32 v27, v66, v70 offset0:8 offset1:24
	ds_write2_b32 v28, v67, v71 offset0:12 offset1:28
	ds_write2_b32 v29, v77, v81 offset0:64 offset1:80
	ds_write2_b32 v30, v78, v82 offset0:68 offset1:84
	ds_write2_b32 v31, v79, v83 offset0:72 offset1:88
	ds_write2_b32 v32, v80, v84 offset0:76 offset1:92
	ds_write2_b32 v40, v93, v97 offset0:128 offset1:144
	ds_write2_b32 v33, v94, v98 offset0:132 offset1:148
	ds_write2_b32 v34, v95, v99 offset0:136 offset1:152
	ds_write2_b32 v36, v96, v100 offset0:140 offset1:156
	ds_write2_b32 v41, v109, v113 offset0:192 offset1:208
	ds_write2_b32 v37, v110, v114 offset0:196 offset1:212
	ds_write2_b32 v38, v111, v115 offset0:200 offset1:216
	ds_write2_b32 v39, v112, v116 offset0:204 offset1:220
	ds_write2_b32 v219, v56, v60 offset0:128 offset1:144
	ds_write2_b32 v26, v57, v61 offset0:132 offset1:148
	ds_write2_b32 v27, v58, v62 offset0:136 offset1:152
	ds_write2_b32 v28, v59, v63 offset0:140 offset1:156
	ds_write2_b32 v29, v54, v74 offset0:192 offset1:208
	ds_write2_b32 v30, v55, v75 offset0:196 offset1:212
	ds_write2_b32 v31, v72, v76 offset0:200 offset1:216
	ds_write2_b32 v32, v73, v35 offset0:204 offset1:220
	ds_write2_b32 v33, v85, v89 offset1:16
	ds_write2_b32 v34, v86, v90 offset0:4 offset1:20
	ds_write2_b32 v36, v87, v91 offset0:8 offset1:24
	ds_write2_b32 v42, v88, v92 offset0:12 offset1:28
	ds_write2_b32 v37, v101, v105 offset0:64 offset1:80
	ds_write2_b32 v38, v102, v106 offset0:68 offset1:84
	ds_write2_b32 v39, v103, v107 offset0:72 offset1:88
	ds_write2_b32 v43, v104, v108 offset0:76 offset1:92
	s_waitcnt lgkmcnt(0)
	s_barrier
	v_mov_b32_e32 v228, 0xbfb8aa3b
	v_mov_b32_e32 v229, 0xbfb8aa3b
	v_mov_b32_e32 v230, 1.0
	v_mov_b32_e32 v231, 1.0
	v_ffbl_b32_e32 v232, v10
	s_branch .LBB0_231

.LBB0_230:
	s_or_b64 exec, exec, s[62:63]
	s_waitcnt lgkmcnt(1)
	v_ashrrev_i32_e32 v6, 31, v14
	v_mov_b32_e32 v8, v14
	v_ashrrev_i32_e32 v9, 31, v14
	v_lshlrev_b64 v[6:7], v232, v[8:9]
	s_addk_i32 s68, 0x2080
	s_waitcnt lgkmcnt(0)
	v_cvt_pk_bf16_f32 v2, v16, v17
	v_cvt_pk_bf16_f32 v3, v18, v19
	v_cvt_pk_bf16_f32 v4, v20, v21
	v_cvt_pk_bf16_f32 v5, v22, v23
	v_lshl_add_u64 v[6:7], v[6:7], 1, v[12:13]
	s_cmpk_eq_u32 s68, 0x8200
	v_add_u32_e32 v14, 8, v14
	global_store_dwordx4 v[6:7], v[2:5], off
	s_cbranch_scc1 .LBB0_84
.LBB0_231:
	v_add_u32_e32 v15, s68, v0
	ds_read_b128 v[6:9], v15
	ds_read_b128 v[2:5], v15 offset:16
	s_and_saveexec_b64 s[62:63], s[6:7]
	s_xor_b64 s[62:63], exec, s[62:63]
	s_cbranch_execz .LBB0_237
	s_waitcnt lgkmcnt(0)
	v_pk_mul_f32 v[16:17], v[6:7], v[228:229]
	v_pk_mul_f32 v[18:19], v[8:9], v[228:229]
	v_pk_mul_f32 v[20:21], v[2:3], v[228:229]
	v_pk_mul_f32 v[22:23], v[4:5], v[228:229]
	v_exp_f32_e32 v16, v16
	v_exp_f32_e32 v17, v17
	v_exp_f32_e32 v18, v18
	v_exp_f32_e32 v19, v19
	v_exp_f32_e32 v20, v20
	v_exp_f32_e32 v21, v21
	v_exp_f32_e32 v22, v22
	v_exp_f32_e32 v23, v23
	v_pk_add_f32 v[16:17], v[16:17], v[230:231]
	v_pk_add_f32 v[18:19], v[18:19], v[230:231]
	v_pk_add_f32 v[20:21], v[20:21], v[230:231]
	v_pk_add_f32 v[22:23], v[22:23], v[230:231]
	v_rcp_f32_e32 v16, v16
	v_rcp_f32_e32 v17, v17
	v_rcp_f32_e32 v18, v18
	v_rcp_f32_e32 v19, v19
	v_rcp_f32_e32 v20, v20
	v_rcp_f32_e32 v21, v21
	v_rcp_f32_e32 v22, v22
	v_rcp_f32_e32 v23, v23
	s_and_b64 vcc, exec, s[10:11]
	s_cbranch_vccz .Lsg_done_c
	v_pk_mul_f32 v[16:17], v[6:7], v[16:17]
	v_pk_mul_f32 v[18:19], v[8:9], v[18:19]
	v_pk_mul_f32 v[20:21], v[2:3], v[20:21]
	v_pk_mul_f32 v[22:23], v[4:5], v[22:23]
.Lsg_done_c:
.LBB0_236:
.LBB0_237:
	s_or_saveexec_b64 s[62:63], s[62:63]
	v_add_u32_e32 v24, -4, v14
	s_xor_b64 exec, exec, s[62:63]
	s_cbranch_execz .LBB0_241
	s_waitcnt lgkmcnt(1)
	v_mul_f32_e32 v16, v7, v7
	v_fmac_f32_e32 v16, v6, v6
	v_fmac_f32_e32 v16, v8, v8
	v_fmac_f32_e32 v16, v9, v9
	s_waitcnt lgkmcnt(0)
	v_fmac_f32_e32 v16, v2, v2
	v_fmac_f32_e32 v16, v3, v3
	v_fmac_f32_e32 v16, v4, v4
	v_fmac_f32_e32 v16, v5, v5
	s_nop 1
	v_add_f32_dpp v16, v16, v16 quad_perm:[1,0,3,2] row_mask:0xf bank_mask:0xf bound_ctrl:1
	s_nop 1
	v_add_f32_dpp v16, v16, v16 quad_perm:[2,3,0,1] row_mask:0xf bank_mask:0xf bound_ctrl:1
	s_nop 1
	v_add_f32_dpp v16, v16, v16 row_half_mirror row_mask:0xf bank_mask:0xf bound_ctrl:1
	s_nop 1
	v_mov_b32_dpp v17, v16 row_mirror row_mask:0xf bank_mask:0xf bound_ctrl:1
	s_and_saveexec_b64 s[64:65], s[8:9]
	s_cbranch_execz .LBB0_240
	v_ashrrev_i32_e32 v25, 31, v24
	v_add_f32_e32 v18, v16, v17
	v_lshl_add_u64 v[16:17], v[24:25], 2, s[36:37]
	global_atomic_add_f32 v[16:17], v18, off

.LBB0_241:
	s_or_b64 exec, exec, s[62:63]
	s_waitcnt lgkmcnt(0)
	v_ashrrev_i32_e32 v2, 31, v24
	v_cvt_pk_bf16_f32 v16, v16, v17
	v_cvt_pk_bf16_f32 v17, v18, v19
	v_cvt_pk_bf16_f32 v19, v22, v23
	v_mov_b32_e32 v23, v2
	ds_read_b128 v[6:9], v15 offset:4160
	ds_read_b128 v[2:5], v15 offset:4176
	v_cvt_pk_bf16_f32 v18, v20, v21
	v_mov_b32_e32 v22, v24
	v_lshlrev_b64 v[20:21], v232, v[22:23]
	v_lshl_add_u64 v[20:21], v[20:21], 1, v[12:13]
	global_store_dwordx4 v[20:21], v[16:19], off
	s_and_saveexec_b64 s[62:63], s[6:7]
	s_xor_b64 s[62:63], exec, s[62:63]
	s_cbranch_execz .LBB0_247
	s_waitcnt lgkmcnt(0)
	v_pk_mul_f32 v[16:17], v[6:7], v[228:229]
	v_pk_mul_f32 v[18:19], v[8:9], v[228:229]
	v_pk_mul_f32 v[20:21], v[2:3], v[228:229]
	v_pk_mul_f32 v[22:23], v[4:5], v[228:229]
	v_exp_f32_e32 v16, v16
	v_exp_f32_e32 v17, v17
	v_exp_f32_e32 v18, v18
	v_exp_f32_e32 v19, v19
	v_exp_f32_e32 v20, v20
	v_exp_f32_e32 v21, v21
	v_exp_f32_e32 v22, v22
	v_exp_f32_e32 v23, v23
	v_pk_add_f32 v[16:17], v[16:17], v[230:231]
	v_pk_add_f32 v[18:19], v[18:19], v[230:231]
	v_pk_add_f32 v[20:21], v[20:21], v[230:231]
	v_pk_add_f32 v[22:23], v[22:23], v[230:231]
	v_rcp_f32_e32 v16, v16
	v_rcp_f32_e32 v17, v17
	v_rcp_f32_e32 v18, v18
	v_rcp_f32_e32 v19, v19
	v_rcp_f32_e32 v20, v20
	v_rcp_f32_e32 v21, v21
	v_rcp_f32_e32 v22, v22
	v_rcp_f32_e32 v23, v23
	s_and_b64 vcc, exec, s[10:11]
	s_cbranch_vccz .Lsg_done_d
	v_pk_mul_f32 v[16:17], v[6:7], v[16:17]
	v_pk_mul_f32 v[18:19], v[8:9], v[18:19]
	v_pk_mul_f32 v[20:21], v[2:3], v[20:21]
	v_pk_mul_f32 v[22:23], v[4:5], v[22:23]
.Lsg_done_d:
.LBB0_246:
.LBB0_247:
	s_andn2_saveexec_b64 s[62:63], s[62:63]
	s_cbranch_execz .LBB0_230
	s_waitcnt lgkmcnt(1)
	v_mul_f32_e32 v15, v7, v7
	v_fmac_f32_e32 v15, v6, v6
	v_fmac_f32_e32 v15, v8, v8
	v_fmac_f32_e32 v15, v9, v9
	s_waitcnt lgkmcnt(0)
	v_fmac_f32_e32 v15, v2, v2
	v_fmac_f32_e32 v15, v3, v3
	v_fmac_f32_e32 v15, v4, v4
	v_fmac_f32_e32 v15, v5, v5
	s_nop 1
	v_add_f32_dpp v15, v15, v15 quad_perm:[1,0,3,2] row_mask:0xf bank_mask:0xf bound_ctrl:1
	s_nop 1
	v_add_f32_dpp v15, v15, v15 quad_perm:[2,3,0,1] row_mask:0xf bank_mask:0xf bound_ctrl:1
	s_nop 1
	v_add_f32_dpp v15, v15, v15 row_half_mirror row_mask:0xf bank_mask:0xf bound_ctrl:1
	s_nop 1
	v_mov_b32_dpp v16, v15 row_mirror row_mask:0xf bank_mask:0xf bound_ctrl:1
	s_and_saveexec_b64 s[64:65], s[8:9]
	s_cbranch_execz .LBB0_229
	v_add_f32_e32 v18, v15, v16
	v_ashrrev_i32_e32 v15, 31, v14
	v_lshl_add_u64 v[16:17], v[14:15], 2, s[36:37]
	global_atomic_add_f32 v[16:17], v18, off
	s_branch .LBB0_229
